# strategy 4: one static s_setprio 1 for waves 4-7 during the attention phase (reset to 0 at the phase end)
# speedup vs baseline: 1.0051x; 1.0051x over previous
; #define LAS __attribute__((address_space(3)))
; __device__ __forceinline__ void xcd_barrier(const XcdBarrier& b) {
;     ...
;     }
;     __syncthreads();
; }
; __global__ void __launch_bounds__(512, 2) fwd(Args a) {
;     ...
;         if (IN(p0 + 4)) { att::attn_phase(a, l, (LAS char*)lds, 0); }
.LBB0_435:
	s_or_b64 exec, exec, s[0:1]
	v_readlane_b32 s16, v252, 18
	v_readlane_b32 s22, v252, 24
	v_readlane_b32 s23, v252, 25
	s_waitcnt lgkmcnt(0)
	s_barrier
	v_readfirstlane_b32 s100, v236
	s_lshr_b32 s100, s100, 6
	s_cmp_ge_u32 s100, 4
	s_cbranch_scc0 .Latt_prio_skip
	s_setprio 1
.Latt_prio_skip:
	v_readlane_b32 s17, v252, 19
	v_readlane_b32 s18, v252, 20
	v_readlane_b32 s19, v252, 21
	v_readlane_b32 s20, v252, 22
	v_readlane_b32 s21, v252, 23

; #define SEAM(k) do { if (IN(k) && (IN((k) + 1) || IN((k) + 2))) { if ((k) == 0) { cg::this_grid().sync(); xbar = xcd_barrier_post((unsigned*)(ws + WS_BAR), bst); xcd_barrier_census(xbar); } else { xcd_barrier(xbar); } } } while (0)
; __device__ __forceinline__ void xcd_barrier(const XcdBarrier& b) {
;     ...
;     }
;     __syncthreads();
; }
; __global__ void __launch_bounds__(512, 2) fwd(Args a) {
;     ...
;         SEAM(p0 + 4);
.LBB0_808:
	s_or_b64 exec, exec, s[0:1]
	s_waitcnt lgkmcnt(0)
	s_barrier
	s_setprio 0

; __global__ void __launch_bounds__(512, 2) fwd(Args a) {
	.amdhsa_kernel _Z3fwd4Args
		.amdhsa_group_segment_fixed_size 0
		.amdhsa_private_segment_fixed_size 0
		.amdhsa_kernarg_size 416
		.amdhsa_user_sgpr_count 2
		.amdhsa_user_sgpr_dispatch_ptr 0
		.amdhsa_user_sgpr_queue_ptr 0
		.amdhsa_user_sgpr_kernarg_segment_ptr 1
		.amdhsa_user_sgpr_dispatch_id 0
		.amdhsa_user_sgpr_kernarg_preload_length 0
		.amdhsa_user_sgpr_kernarg_preload_offset 0
		.amdhsa_user_sgpr_private_segment_size 0
		.amdhsa_uses_dynamic_stack 0
		.amdhsa_enable_private_segment 0
		.amdhsa_system_sgpr_workgroup_id_x 1
		.amdhsa_system_sgpr_workgroup_id_y 0
		.amdhsa_system_sgpr_workgroup_id_z 0
		.amdhsa_system_sgpr_workgroup_info 0
		.amdhsa_system_vgpr_workitem_id 2
		.amdhsa_next_free_vgpr 256
		.amdhsa_next_free_sgpr 102
		.amdhsa_accum_offset 256
		.amdhsa_reserve_vcc 1
		.amdhsa_float_round_mode_32 0
		.amdhsa_float_round_mode_16_64 0
		.amdhsa_float_denorm_mode_32 3
		.amdhsa_float_denorm_mode_16_64 3
		.amdhsa_dx10_clamp 1
		.amdhsa_ieee_mode 1
		.amdhsa_fp16_overflow 0
		.amdhsa_tg_split 0
		.amdhsa_exception_fp_ieee_invalid_op 0
		.amdhsa_exception_fp_denorm_src 0
		.amdhsa_exception_fp_ieee_div_zero 0
		.amdhsa_exception_fp_ieee_overflow 0
		.amdhsa_exception_fp_ieee_underflow 0
		.amdhsa_exception_fp_ieee_inexact 0
		.amdhsa_exception_int_div_zero 0
	.end_amdhsa_kernel

; __global__ void __launch_bounds__(512, 2) fwd(Args a) {
amdhsa.kernels:
  - .agpr_count:     0
    .args:
      - .offset:         0
        .size:           160
        .value_kind:     by_value
      - .offset:         160
        .size:           4
        .value_kind:     hidden_block_count_x
      - .offset:         164
        .size:           4
        .value_kind:     hidden_block_count_y
      - .offset:         168
        .size:           4
        .value_kind:     hidden_block_count_z
      - .offset:         172
        .size:           2
        .value_kind:     hidden_group_size_x
      - .offset:         174
        .size:           2
        .value_kind:     hidden_group_size_y
      - .offset:         176
        .size:           2
        .value_kind:     hidden_group_size_z
      - .offset:         178
        .size:           2
        .value_kind:     hidden_remainder_x
      - .offset:         180
        .size:           2
        .value_kind:     hidden_remainder_y
      - .offset:         182
        .size:           2
        .value_kind:     hidden_remainder_z
      - .offset:         200
        .size:           8
        .value_kind:     hidden_global_offset_x
      - .offset:         208
        .size:           8
        .value_kind:     hidden_global_offset_y
      - .offset:         216
        .size:           8
        .value_kind:     hidden_global_offset_z
      - .offset:         224
        .size:           2
        .value_kind:     hidden_grid_dims
      - .offset:         248
        .size:           8
        .value_kind:     hidden_multigrid_sync_arg
      - .offset:         280
        .size:           4
        .value_kind:     hidden_dynamic_lds_size
    .group_segment_fixed_size: 0
    .kernarg_segment_align: 8
    .kernarg_segment_size: 416
    .language:       OpenCL C
    .language_version:
      - 2
      - 0
    .max_flat_workgroup_size: 512
    .name:           _Z3fwd4Args
    .private_segment_fixed_size: 0
    .sgpr_count:     108
    .sgpr_spill_count: 257
    .symbol:         _Z3fwd4Args.kd
    .uniform_work_group_size: 1
    .uses_dynamic_stack: false
    .vgpr_count:     256
    .vgpr_spill_count: 0
    .wavefront_size: 64
